# P6|P7 grid barrier replaced by chain-done flags + queue of mLSTM output item groups (idle workgroups start output items early); P7|P8 seam now grid; plus barrier invalidate on wave 1
# speedup vs baseline: 1.0075x; 1.0075x over previous
.Lchain_pub:
	s_waitcnt vmcnt(0)
	s_barrier
	s_and_saveexec_b64 s[98:99], s[44:45]
	s_cbranch_execz .Lchain_pub_done
	buffer_wbl2 sc1
	s_waitcnt vmcnt(0)
	s_lshr_b32 s100, s54, 5
	s_lshl_b32 s100, s100, 1
	s_bfe_u32 s101, s54, 0x10002
	s_add_i32 s100, s100, s101
	s_lshl_b32 s100, s100, 8
	s_add_i32 s100, s100, 0x800
	v_mov_b32_e32 v250, s100
	v_mov_b32_e32 v251, 1
	global_atomic_add v250, v251, s[46:47]
	s_waitcnt vmcnt(0)
.Lchain_pub_done:
	s_or_b64 exec, exec, s[98:99]
	s_branch .LBB0_1077
.Lp7_pull_init:
	s_and_b64 vcc, exec, s[4:5]
	s_cbranch_vccnz .LBB0_1177
	s_mov_b32 s99, s54
.Lp7_pull:
	s_waitcnt lgkmcnt(0)
	s_barrier
	s_and_saveexec_b64 s[100:101], s[44:45]
	s_cbranch_execz .Lp7_got
	v_mov_b32_e32 v250, 0x400
	v_mov_b32_e32 v251, 1
	global_atomic_add v250, v250, v251, s[46:47] sc0
	s_waitcnt vmcnt(0)
	v_mov_b32_e32 v251, 0x24184
	ds_write_b32 v251, v250
	s_waitcnt lgkmcnt(0)
.Lp7_got:
	s_or_b64 exec, exec, s[100:101]
	s_barrier
	v_mov_b32_e32 v251, 0x24184
	ds_read_b32 v250, v251
	s_waitcnt lgkmcnt(0)
	s_nop 0
	v_readfirstlane_b32 s98, v250
	s_nop 0
	s_cmp_ge_u32 s98, 0x100
	s_cbranch_scc1 .Lp7_done
	s_mov_b32 s54, s98
	s_lshr_b32 s100, s54, 5
	s_lshl_b32 s100, s100, 3
	s_and_b32 s101, s54, 7
	s_add_i32 s100, s100, s101
	s_lshr_b32 s100, s100, 4
	s_lshl_b32 s100, s100, 2
	s_bfe_u32 s101, s54, 0x20003
	s_add_i32 s100, s100, s101
	s_lshl_b32 s100, s100, 8
	s_add_i32 s100, s100, 0x800
	v_mov_b32_e32 v251, s100
	s_and_saveexec_b64 s[100:101], s[44:45]
	s_cbranch_execz .Lp7_ready
	s_mov_b32 s98, 0
.Lp7_poll:
	global_load_dword v250, v251, s[46:47] sc1
	s_waitcnt vmcnt(0)
	v_cmp_gt_u32_e32 vcc, 4, v250
	s_cbranch_vccz .Lp7_acq
	s_sleep 4
	s_add_i32 s98, s98, 1
	s_cmp_lt_u32 s98, 0x20000
	s_cbranch_scc1 .Lp7_poll
.Lp7_acq:
	buffer_inv sc1
	s_waitcnt vmcnt(0)
.Lp7_ready:
	s_or_b64 exec, exec, s[100:101]
	s_barrier
	s_mov_b64 s[58:59], s[0:1]
	v_mov_b32_e32 v172, v0
	s_branch .Lp7_body
.Lp7_done:
	s_mov_b32 s54, s99
	s_mov_b64 s[8:9], -1
	s_branch .LBB0_1671

.LBB0_1364:
	s_or_b64 exec, exec, s[8:9]
.LBB0_1365:
	s_or_b64 exec, exec, s[22:23]
	s_mov_b64 s[58:59], s[0:1]
	v_mov_b32_e32 v172, v0
	s_waitcnt lgkmcnt(0)
	s_barrier
.Lp7_body:
	s_mov_b64 s[8:9], -1
	v_readfirstlane_b32 s71, v172
	v_and_b32_e32 v171, 63, v172
	s_ashr_i32 s70, s71, 6
	s_and_b64 vcc, exec, s[4:5]
	v_lshlrev_b32_e32 v196, 3, v172
	v_ashrrev_i32_e32 v166, 4, v172
	s_cbranch_vccnz .LBB0_1550
	s_ashr_i32 s25, s54, 4
	s_load_dwordx2 s[34:35], s[58:59], 0x90
	s_and_b32 s8, s25, -4
	s_bfe_u32 s24, s54, 0x20003
	s_or_b32 s60, s8, s24
	s_lshl_b32 s8, s54, 2
	s_and_b32 s8, s8, 28
	s_and_b32 s9, s54, 32
	s_ashr_i32 s20, s54, 6
	s_or_b32 s22, s8, s9
	s_ashr_i32 s21, s20, 31
	s_waitcnt lgkmcnt(0)
	s_add_u32 s76, s34, 0x3000000
	s_addc_u32 s77, s35, 0
	s_lshl_b64 s[8:9], s[20:21], 22
	s_add_u32 s8, s76, s8
	s_addc_u32 s9, s77, s9
	s_lshl_b32 s10, s22, 16
	s_add_u32 s8, s8, s10
	s_addc_u32 s9, s9, 0
	s_lshl_b32 s10, s24, 8
	s_add_u32 s8, s8, s10
	s_addc_u32 s9, s9, 0
	s_add_u32 s74, s34, 0xd000000
	s_addc_u32 s75, s35, 0
	s_ashr_i32 s61, s60, 31
	s_lshl_b64 s[10:11], s[60:61], 6
	s_or_b32 s10, s10, s22
	s_lshl_b64 s[12:13], s[10:11], 14
	s_add_u32 s14, s74, s12
	s_addc_u32 s15, s75, s13
	s_add_u32 s78, s34, 0xe000000
	s_addc_u32 s79, s35, 0
	v_and_b32_e32 v2, 0x78, v196
	s_add_u32 s12, s78, s12
	s_waitcnt vmcnt(2)
	v_mov_b32_e32 v62, 0
	v_lshlrev_b32_e32 v180, 1, v2
	v_and_b32_e32 v2, 56, v196
	v_and_b32_e32 v6, 0xffffffc0, v196
	s_addc_u32 s13, s79, s13
	v_mov_b32_e32 v181, v62
	v_lshlrev_b32_e32 v182, 1, v2
	v_mov_b32_e32 v183, v62
	v_ashrrev_i32_e32 v167, 31, v166
	v_ashrrev_i32_e32 v7, 31, v6
	v_lshl_add_u64 v[4:5], s[8:9], 0, v[180:181]
	v_lshl_add_u64 v[8:9], s[12:13], 0, v[182:183]
	v_lshlrev_b64 v[184:185], 10, v[166:167]
	v_lshlrev_b64 v[186:187], 1, v[6:7]
	v_lshl_add_u64 v[2:3], v[4:5], 0, v[184:185]
	v_lshl_add_u64 v[6:7], v[8:9], 0, v[186:187]
	global_load_dwordx4 v[46:49], v[2:3], off nt
	global_load_dwordx4 v[50:53], v[6:7], off nt
	v_add_u32_e32 v6, 0x200, v172
	v_ashrrev_i32_e32 v2, 4, v6
	v_ashrrev_i32_e32 v3, 31, v2
	v_lshl_add_u64 v[10:11], s[14:15], 0, v[182:183]
	v_lshlrev_b64 v[188:189], 10, v[2:3]
	v_lshl_add_u64 v[12:13], v[10:11], 0, v[186:187]
	v_lshl_add_u64 v[4:5], v[4:5], 0, v[188:189]
	v_lshlrev_b32_e32 v223, 3, v6
	global_load_dwordx4 v[54:57], v[12:13], off nt
	global_load_dwordx4 v[58:61], v[4:5], off nt
	v_and_b32_e32 v4, 0xffffffc0, v223
	v_ashrrev_i32_e32 v5, 31, v4
	v_lshlrev_b64 v[190:191], 1, v[4:5]
	v_lshl_add_u64 v[4:5], v[8:9], 0, v[190:191]
	v_lshl_add_u64 v[8:9], v[10:11], 0, v[190:191]
	global_load_dwordx4 v[66:69], v[4:5], off nt
	global_load_dwordx4 v[70:73], v[8:9], off nt
	s_mul_i32 s8, s10, 0x8100
	s_mul_hi_u32 s9, s10, 0x8100
	s_mul_i32 s10, s11, 0x8100
	s_add_i32 s9, s9, s10
	s_add_u32 s80, s34, 0x9000000
	s_addc_u32 s81, s35, 0
	s_add_u32 s8, s80, s8
	s_addc_u32 s9, s81, s9
	v_lshl_add_u64 v[4:5], s[8:9], 0, v[180:181]
	s_movk_i32 s8, 0x810
	v_cmp_gt_i32_e64 s[8:9], s8, v172
	s_waitcnt vmcnt(7)
	v_mov_b32_e32 v74, 0
	v_mov_b32_e32 v75, v62
	v_mov_b32_e32 v76, v62
	v_mov_b32_e32 v77, v62
	s_and_saveexec_b64 s[10:11], s[8:9]
	s_cbranch_execz .LBB0_1368
	v_and_b32_e32 v8, 0xffffff80, v196
	v_ashrrev_i32_e32 v9, 31, v8
	v_lshl_add_u64 v[8:9], v[8:9], 1, v[4:5]
	global_load_dwordx4 v[74:77], v[8:9], off nt

.LBB0_1549:
	s_or_b64 exec, exec, s[8:9]
	s_waitcnt lgkmcnt(0)
	s_barrier
	ds_read_b32 v42, v216
	ds_read_b32 v43, v218 offset:256
	v_permlane16_swap_b32_e32 v40, v36
	v_permlane16_swap_b32_e32 v41, v37
	s_waitcnt lgkmcnt(0)
	v_add_f32_e32 v42, v42, v43
	v_mov_b32_e32 v43, 0x358637bd
	v_fmac_f32_e32 v43, 0x3c000000, v42
	v_rsq_f32_e32 v42, v43
	s_waitcnt vmcnt(3)
	v_lshlrev_b32_e32 v43, 16, v18
	v_and_b32_e32 v18, 0xffff0000, v18
	v_mul_f32_e32 v18, 0xbfb8aa3b, v18
	v_mul_f32_e32 v43, 0xbfb8aa3b, v43
	v_exp_f32_e32 v18, v18
	v_exp_f32_e32 v43, v43
	v_permlane16_swap_b32_e32 v38, v34
	v_add_f32_e32 v18, 1.0, v18
	v_add_f32_e32 v43, 1.0, v43
	v_rcp_f32_e32 v49, v18
	v_lshlrev_b32_e32 v18, 16, v19
	v_pk_mul_f32 v[40:41], v[42:43], v[40:41] op_sel_hi:[0,1]
	v_mul_f32_e32 v18, 0xbfb8aa3b, v18
	v_pk_mul_f32 v[22:23], v[22:23], v[40:41]
	v_exp_f32_e32 v40, v18
	v_and_b32_e32 v18, 0xffff0000, v19
	v_mul_f32_e32 v18, 0xbfb8aa3b, v18
	v_permlane16_swap_b32_e32 v39, v35
	v_rcp_f32_e32 v48, v43
	v_exp_f32_e32 v41, v18
	v_pk_mul_f32 v[38:39], v[42:43], v[38:39] op_sel_hi:[0,1]
	v_pk_mul_f32 v[24:25], v[24:25], v[38:39]
	v_lshlrev_b32_e32 v38, 16, v20
	v_and_b32_e32 v20, 0xffff0000, v20
	v_mul_f32_e32 v20, 0xbfb8aa3b, v20
	v_pk_mul_f32 v[18:19], v[48:49], v[22:23]
	v_add_f32_e32 v22, 1.0, v40
	v_add_f32_e32 v23, 1.0, v41
	v_exp_f32_e32 v20, v20
	v_rcp_f32_e32 v22, v22
	v_rcp_f32_e32 v23, v23
	v_mul_f32_e32 v38, 0xbfb8aa3b, v38
	v_add_f32_e32 v20, 1.0, v20
	v_exp_f32_e32 v38, v38
	v_pk_mul_f32 v[22:23], v[22:23], v[24:25]
	v_rcp_f32_e32 v25, v20
	v_lshlrev_b32_e32 v20, 16, v21
	v_and_b32_e32 v21, 0xffff0000, v21
	v_mul_f32_e32 v20, 0xbfb8aa3b, v20
	v_mul_f32_e32 v21, 0xbfb8aa3b, v21
	v_exp_f32_e32 v20, v20
	v_exp_f32_e32 v21, v21
	v_add_f32_e32 v24, 1.0, v38
	v_rcp_f32_e32 v24, v24
	v_lshlrev_b64 v[44:45], 11, v[78:79]
	v_add_f32_e32 v20, 1.0, v20
	v_add_f32_e32 v21, 1.0, v21
	v_lshl_add_u64 v[44:45], s[34:35], 0, v[44:45]
	v_pk_mul_f32 v[36:37], v[42:43], v[36:37] op_sel_hi:[0,1]
	v_rcp_f32_e32 v20, v20
	v_rcp_f32_e32 v21, v21
	v_lshl_add_u64 v[44:45], v[44:45], 0, s[36:37]
	v_pk_mul_f32 v[14:15], v[14:15], v[36:37]
	v_lshl_add_u64 v[44:45], v[168:169], 1, v[44:45]
	s_mov_b64 s[8:9], 0x5000400
	v_pk_mul_f32 v[24:25], v[24:25], v[14:15]
	v_pk_mul_f32 v[14:15], v[42:43], v[34:35] op_sel_hi:[0,1]
	v_lshl_add_u64 v[46:47], v[44:45], 0, s[8:9]
	v_pk_mul_f32 v[14:15], v[16:17], v[14:15]
	s_mov_b32 s8, 0x5000000
	v_pk_mul_f32 v[20:21], v[20:21], v[14:15]
	v_cvt_pk_bf16_f32 v14, v18, v19
	v_add_co_u32_e32 v18, vcc, s8, v44
	v_cvt_pk_bf16_f32 v15, v22, v23
	v_cvt_pk_bf16_f32 v16, v24, v25
	v_cvt_pk_bf16_f32 v17, v20, v21
	v_addc_co_u32_e32 v19, vcc, 0, v45, vcc
	global_store_dwordx4 v[18:19], v[14:17], off offset:1024
	v_permlane16_swap_b32_e32 v32, v28
	s_waitcnt vmcnt(3)
	v_lshlrev_b32_e32 v14, 16, v6
	v_and_b32_e32 v6, 0xffff0000, v6
	v_mul_f32_e32 v6, 0xbfb8aa3b, v6
	v_mul_f32_e32 v14, 0xbfb8aa3b, v14
	v_exp_f32_e32 v6, v6
	v_exp_f32_e32 v14, v14
	v_permlane16_swap_b32_e32 v33, v29
	v_add_f32_e32 v6, 1.0, v6
	v_add_f32_e32 v14, 1.0, v14
	v_rcp_f32_e32 v15, v6
	v_lshlrev_b32_e32 v6, 16, v7
	v_rcp_f32_e32 v14, v14
	v_pk_mul_f32 v[16:17], v[42:43], v[32:33] op_sel_hi:[0,1]
	v_mul_f32_e32 v6, 0xbfb8aa3b, v6
	s_waitcnt vmcnt(1)
	v_pk_mul_f32 v[10:11], v[10:11], v[16:17]
	v_exp_f32_e32 v16, v6
	v_and_b32_e32 v6, 0xffff0000, v7
	v_mul_f32_e32 v6, 0xbfb8aa3b, v6
	v_permlane16_swap_b32_e32 v30, v26
	v_permlane16_swap_b32_e32 v31, v27
	v_exp_f32_e32 v17, v6
	v_pk_mul_f32 v[6:7], v[14:15], v[10:11]
	v_pk_mul_f32 v[14:15], v[42:43], v[30:31] op_sel_hi:[0,1]
	v_pk_mul_f32 v[12:13], v[12:13], v[14:15]
	v_lshlrev_b32_e32 v14, 16, v8
	v_and_b32_e32 v8, 0xffff0000, v8
	v_mul_f32_e32 v8, 0xbfb8aa3b, v8
	v_add_f32_e32 v10, 1.0, v16
	v_add_f32_e32 v11, 1.0, v17
	v_exp_f32_e32 v8, v8
	v_rcp_f32_e32 v10, v10
	v_rcp_f32_e32 v11, v11
	v_mul_f32_e32 v14, 0xbfb8aa3b, v14
	v_add_f32_e32 v8, 1.0, v8
	v_and_b32_e32 v18, 0xffff0000, v9
	v_exp_f32_e32 v14, v14
	v_pk_mul_f32 v[10:11], v[10:11], v[12:13]
	v_rcp_f32_e32 v13, v8
	v_lshlrev_b32_e32 v8, 16, v9
	v_mul_f32_e32 v8, 0xbfb8aa3b, v8
	v_mul_f32_e32 v9, 0xbfb8aa3b, v18
	v_exp_f32_e32 v8, v8
	v_exp_f32_e32 v9, v9
	v_add_f32_e32 v12, 1.0, v14
	v_rcp_f32_e32 v12, v12
	v_add_f32_e32 v8, 1.0, v8
	v_add_f32_e32 v9, 1.0, v9
	v_pk_mul_f32 v[14:15], v[42:43], v[28:29] op_sel_hi:[0,1]
	v_rcp_f32_e32 v8, v8
	v_rcp_f32_e32 v9, v9
	v_pk_mul_f32 v[2:3], v[2:3], v[14:15]
	s_mov_b64 s[8:9], 0
	v_pk_mul_f32 v[12:13], v[12:13], v[2:3]
	v_pk_mul_f32 v[2:3], v[42:43], v[26:27] op_sel_hi:[0,1]
	v_pk_mul_f32 v[2:3], v[4:5], v[2:3]
	v_cvt_pk_bf16_f32 v4, v12, v13
	v_pk_mul_f32 v[8:9], v[8:9], v[2:3]
	v_cvt_pk_bf16_f32 v2, v6, v7
	v_cvt_pk_bf16_f32 v3, v10, v11
	v_cvt_pk_bf16_f32 v5, v8, v9
	global_store_dwordx4 v[46:47], v[2:5], off offset:64
	s_barrier
	s_branch .Lp7_pull
